# P3 entry stagger: workgroups of odd row blocks sleep ~8 us so their epilogue bursts interleave with the even row blocks' main loops
# baseline (speedup 1.0000x reference)
.LBB0_278:
	s_load_dwordx4 s[12:15], s[96:97], 0x140
	s_cmp_lt_i32 s84, 5
	s_cselect_b64 s[0:1], -1, 0
	s_and_b64 s[0:1], s[0:1], s[2:3]
	s_andn2_b64 vcc, exec, s[0:1]
	s_cbranch_vccnz .LBB0_298
	s_cmpk_gt_i32 s10, 0xff
	s_cbranch_scc1 .LBB0_298
	s_bitcmp1_b32 s10, 5
	s_cbranch_scc0 .Lstag_p3
	s_sleep 127
	s_sleep 127
.Lstag_p3:
	v_lshlrev_b32_e32 v5, 6, v0
	v_and_b32_e32 v4, 48, v0
	v_and_b32_e32 v6, 0x3c0, v5
	v_lshlrev_b32_e32 v8, 2, v0
	v_or_b32_e32 v7, v6, v4
	v_and_b32_e32 v8, 32, v8
	s_mov_b32 s0, 0x14000
	v_bitop3_b32 v9, v7, s0, v8 bitop3:0xde
	s_mov_b32 s0, 0x18000
	v_lshrrev_b32_e32 v3, 8, v0
	s_mov_b32 s11, 0x10000
	v_bitop3_b32 v10, v7, s0, v8 bitop3:0xde
	s_mov_b32 s0, 0x1c000
	s_add_u32 s33, s94, 0x1000
	v_cmp_eq_u32_e32 vcc, 1, v3
	v_bitop3_b32 v4, v6, v8, v4 bitop3:0x36
	v_bitop3_b32 v6, v7, s11, v8 bitop3:0xde
	v_bitop3_b32 v7, v7, s0, v8 bitop3:0xde
	v_lshlrev_b32_e32 v3, 13, v3
	s_movk_i32 s0, 0x100
	s_addc_u32 s60, s95, 0
	v_and_b32_e32 v2, 15, v0
	v_lshrrev_b32_e32 v1, 2, v0
	v_and_b32_e32 v5, 0x3000, v5
	v_or_b32_e32 v8, 0x800, v3
	v_or_b32_e32 v11, 0x1000, v3
	v_or_b32_e32 v12, 0x1800, v3
	v_cmp_gt_u32_e64 s[2:3], s0, v0
	s_add_u32 s8, s96, 0x188
	v_lshrrev_b32_e32 v13, 1, v0
	s_movk_i32 s0, 0x60
	v_and_b32_e32 v1, 0x4c, v1
	v_cmp_eq_u32_e64 s[4:5], 0, v0
	s_addc_u32 s9, s97, 0
	v_and_or_b32 v160, v13, s0, v2
	v_mov_b32_e32 v131, 0
	s_mov_b64 s[16:17], 0x80
	s_mov_b32 s61, 0x8000
	s_mov_b64 s[18:19], 0x20080
	v_add_u32_e32 v161, v6, v5
	v_add_u32_e32 v162, v4, v3
	v_add_u32_e32 v163, v4, v8
	v_add_u32_e32 v164, v4, v11
	v_add_u32_e32 v165, v4, v12
	v_add_u32_e32 v166, v9, v5
	s_mov_b64 s[20:21], 0x100
	s_mov_b64 s[22:23], 0x20100
	v_add_u32_e32 v167, v10, v5
	v_add_u32_e32 v168, v7, v5
	s_mov_b64 s[26:27], 0x180
	s_mov_b64 s[28:29], 0x20180
	s_mov_b32 s62, 0x80000
	s_mov_b32 s63, 0x90000
	s_mov_b32 s64, 0x40000
	s_mov_b32 s65, 0x48000
	s_mov_b64 s[30:31], 0x40080
	s_mov_b64 s[34:35], 0x40100
	s_mov_b64 s[46:47], 0x40180
	v_mov_b32_e32 v169, 1
	s_mov_b32 s66, s10
	s_branch .LBB0_282
